# weight-conversion unit: both f32 row loads issued before the LDS-reuse barrier
# speedup vs baseline: 1.2675x; 1.0001x over previous
; DI int otid() { int t = threadIdx.x & 255; asm volatile("" : "+v"(t)); return t; }
; DI void conv_unit(const float* __restrict__ src, int ld, int col0, int k0, h16* __restrict__ dst, int K, int n0, h16* lds) {
;   const int t = otid();
;   __syncthreads();
;   {
;     const int c4 = (t & 7) * 4, kq = t >> 3;
; #pragma unroll
;     for (int i = 0; i < 2; ++i) {
;       const int kk = kq + 32 * i;
;       const f4v v = *(const f4v*)&src[(size_t)(k0 + kk) * ld + col0 + c4];
;       lds[(c4 + 0) * LDH + kk] = (h16)v[0]; lds[(c4 + 1) * LDH + kk] = (h16)v[1];
;       lds[(c4 + 2) * LDH + kk] = (h16)v[2]; lds[(c4 + 3) * LDH + kk] = (h16)v[3];
;     }
;   }
;   __syncthreads();
;   {
;     const int c = t >> 3, ks = (t & 7) * 8;
;     *(u4v*)&dst[(size_t)(n0 + c) * K + k0 + ks] = *(const u4v*)&lds[c * LDH + ks];
;   }
; }
.LBB0_894:
	s_or_b64 exec, exec, s[2:3]
	v_and_b32_e32 v14, 7, v182
	v_ashrrev_i32_e32 v18, 3, v182
	v_ashrrev_i32_e32 v9, 31, v8
	v_lshl_add_u64 v[12:13], v[8:9], 2, v[12:13]
	v_lshlrev_b32_e32 v8, 4, v14
	v_mov_b32_e32 v9, v0
	v_add_u32_e32 v20, v18, v2
	v_lshl_add_u64 v[16:17], v[12:13], 0, v[8:9]
	v_ashrrev_i32_e32 v12, 31, v20
	v_mul_lo_u32 v26, v10, v12
	v_mul_lo_u32 v15, v11, v20
	v_mad_u64_u32 v[12:13], s[2:3], v10, v20, 0
	v_add3_u32 v13, v13, v26, v15
	v_lshl_add_u64 v[12:13], v[12:13], 2, v[16:17]
	v_add_u32_e32 v26, 32, v20
	v_ashrrev_i32_e32 v27, 31, v26
	v_mul_lo_u32 v27, v10, v27
	v_mul_lo_u32 v38, v11, v26
	v_mad_u64_u32 v[28:29], s[2:3], v10, v26, 0
	v_add3_u32 v29, v29, v27, v38
	v_lshl_add_u64 v[28:29], v[28:29], 2, v[16:17]
	global_load_dwordx4 v[30:33], v[12:13], off
	global_load_dwordx4 v[34:37], v[28:29], off
	v_add_u32_e32 v3, v18, v3
	v_mul_lo_u32 v15, v7, v3
	v_ashrrev_i32_e32 v26, 31, v3
	v_mul_lo_u32 v26, v6, v26
	v_mad_u64_u32 v[6:7], s[2:3], v6, v3, 0
	v_add3_u32 v7, v7, v26, v15
	v_mov_b32_e32 v3, v0
	v_lshl_add_u64 v[4:5], v[6:7], 1, v[4:5]
	v_lshl_add_u64 v[2:3], v[2:3], 1, v[4:5]
	v_lshl_add_u64 v[2:3], v[2:3], 0, v[8:9]
	v_mul_u32_u24_e32 v19, 0x120, v14
	v_lshlrev_b32_e32 v19, 1, v19
	v_lshlrev_b32_e32 v21, 1, v18
	v_add3_u32 v22, v183, v19, v21
	v_mul_lo_u32 v10, v18, s33
	v_add3_u32 v10, v183, v10, v8
	s_barrier
	s_waitcnt vmcnt(1)
	v_cvt_f16_f32_e32 v30, v30
	v_cvt_f16_f32_e32 v31, v31
	v_cvt_f16_f32_e32 v32, v32
	v_cvt_f16_f32_e32 v33, v33
	ds_write_b16 v22, v30
	ds_write_b16 v22, v31 offset:144
	ds_write_b16 v22, v32 offset:288
	ds_write_b16 v22, v33 offset:432
	s_waitcnt vmcnt(0)
	v_cvt_f16_f32_e32 v34, v34
	v_cvt_f16_f32_e32 v35, v35
	v_cvt_f16_f32_e32 v36, v36
	v_cvt_f16_f32_e32 v37, v37
	ds_write_b16 v22, v34 offset:64
	ds_write_b16 v22, v35 offset:208
	ds_write_b16 v22, v36 offset:352
	ds_write_b16 v22, v37 offset:496
	s_waitcnt lgkmcnt(0)
	s_barrier
	ds_read_b128 v[10:13], v10
	s_waitcnt lgkmcnt(0)
	global_store_dwordx4 v[2:3], v[10:13], off
